# scan: consumer waves at priority 2 instead of 3 (knob now wired; immediate-only change)
# baseline (speedup 1.0000x reference)
; __device__ __forceinline__ void phase_scan2(const Params& p, int l, LAS unsigned char* lds) {
;     ...
;         auto consume = [&](int c, LAS const unsigned char* sl) {
;             const bf16x8 s0 = __builtin_bit_cast(bf16x8, (u32x4){pk_bf16(ST[0][0], ST[0][1]), pk_bf16(ST[0][2], ST[0][3]), pk_bf16(ST[1][0], ST[1][1]), pk_bf16(ST[1][2], ST[1][3])});
;             const bf16x8 s1 = __builtin_bit_cast(bf16x8, (u32x4){pk_bf16(ST[2][0], ST[2][1]), pk_bf16(ST[2][2], ST[2][3]), pk_bf16(ST[3][0], ST[3][1]), pk_bf16(ST[3][2], ST[3][3])});
;             const bf16x8 at0 = *(LAS const bf16x8*)(sl + SC_AT + (fr * 32 + fq * 8) * 2), at1 = *(LAS const bf16x8*)(sl + SC_AT + ((16 + fr) * 32 + fq * 8) * 2);
;             const bf16x8 rt0 = *(LAS const bf16x8*)(sl + SC_RT + (fr * 32 + fq * 8) * 2), rt1 = *(LAS const bf16x8*)(sl + SC_RT + ((16 + fr) * 32 + fq * 8) * 2);
;             const int mo = (fr * 16 + 4 * fq) * 2;
;             const bf16x8 vf = frag4(sl + SC_VP + mo), akf = frag4(sl + SC_AK + mo), xf = frag4(sl + SC_X + mo), rbf = frag4(sl + SC_RB + mo), rkf = frag4(sl + SC_RK + mo);
;             const f32x4 z = (f32x4){0.f, 0.f, 0.f, 0.f};
;             f32x4 g = __builtin_amdgcn_mfma_f32_16x16x32_bf16(at0, s0, z, 0, 0, 0);
;             g = __builtin_amdgcn_mfma_f32_16x16x32_bf16(at1, s1, g, 0, 0, 0);
;             g = __builtin_amdgcn_mfma_f32_16x16x32_bf16(akf, vf, g, 0, 0, 0);
;             const f32x4 sa = __builtin_amdgcn_mfma_f32_16x16x32_bf16(xf, cfrag(g), z, 0, 0, 0);
;             const bf16x8 saf = cfrag(sa);
;             f32x4 y = __builtin_amdgcn_mfma_f32_16x16x32_bf16(rt0, s0, z, 0, 0, 0);
;             y = __builtin_amdgcn_mfma_f32_16x16x32_bf16(rt1, s1, y, 0, 0, 0);
;             y = __builtin_amdgcn_mfma_f32_16x16x32_bf16(rbf, saf, y, 0, 0, 0);
;             y = __builtin_amdgcn_mfma_f32_16x16x32_bf16(rkf, vf, y, 0, 0, 0);
; #pragma unroll
;             for (int jt = 0; jt < 4; ++jt) {
;                 const f32x4 wc = *(LAS const f32x4*)(sl + SC_WC + (16 * jt + 4 * fq) * 4);
;                 const bf16x8 bb = frag4(sl + SC_BBT + ((16 * jt + fr) * SC_BS + 4 * fq) * 2), kb = frag4(sl + SC_KBT + ((16 * jt + fr) * SC_BS + 4 * fq) * 2);
;                 f32x4 acc = ST[jt];
;                 acc = __builtin_amdgcn_mfma_f32_16x16x32_bf16(bb, saf, acc, 0, 0, 0);
;                 acc = __builtin_amdgcn_mfma_f32_16x16x32_bf16(kb, vf, acc, 0, 0, 0);
.Lsc_consumer:
	s_setprio 2
	v_and_b32_e32 v4, 7, v1
	s_lshr_b32 s1, s25, 2
	v_xor_b32_e32 v4, v4, v2
	s_mul_i32 s0, s1, 768
	v_lshlrev_b32_e32 v4, 4, v4
	v_and_b32_e32 v5, 3, v1
	v_lshl_add_u32 v163, v1, 7, v4
	v_lshrrev_b32_e32 v4, 2, v1
	v_add_u32_e32 v13, s0, v6
	v_lshl_add_u32 v4, v2, 2, v4
	s_add_u32 s53, s53, s1
	v_and_b32_e32 v165, 7, v4
	s_mul_i32 s0, s54, 4096
	v_xor_b32_e32 v165, v165, v5
	s_lshl_b32 s0, s0, 10
	v_lshlrev_b32_e32 v165, 4, v165
	s_lshl_b32 s14, s52, 7
	v_lshl_add_u32 v165, v4, 7, v165
	s_lshl_b32 s15, s53, 5
	s_add_u32 s0, s0, s14
	v_lshlrev_b32_e32 v164, 5, v2
	v_add_u32_e32 v165, 4096, v165
	v_lshlrev_b32_e32 v166, 12, v2
	s_add_u32 s0, s0, s15
	s_add_u32 s0, s0, 0x5000000
	v_mov_b32_e32 v8, 0
	v_mov_b32_e32 v116, 0
	v_mov_b32_e32 v9, 0
	v_mov_b32_e32 v117, 0
	v_mov_b32_e32 v10, 0
	v_mov_b32_e32 v118, 0
	v_mov_b32_e32 v11, 0
	v_mov_b32_e32 v119, 0
	v_mov_b32_e32 v16, 0
	v_mov_b32_e32 v120, 0
	v_mov_b32_e32 v17, 0
	v_mov_b32_e32 v121, 0
	v_mov_b32_e32 v18, 0
	v_mov_b32_e32 v122, 0
	v_mov_b32_e32 v19, 0
	v_mov_b32_e32 v123, 0
	v_mov_b32_e32 v20, 0
	v_mov_b32_e32 v124, 0
	v_mov_b32_e32 v21, 0
	v_mov_b32_e32 v125, 0
	v_mov_b32_e32 v22, 0
	v_mov_b32_e32 v126, 0
	v_mov_b32_e32 v23, 0
	v_mov_b32_e32 v127, 0
	v_mov_b32_e32 v24, 0
	v_mov_b32_e32 v128, 0
	v_mov_b32_e32 v25, 0
	v_mov_b32_e32 v129, 0
	v_mov_b32_e32 v26, 0
	v_mov_b32_e32 v130, 0
	v_mov_b32_e32 v27, 0
	v_mov_b32_e32 v131, 0
	v_xor_b32_e32 v169, 64, v163
	v_add_u32_e32 v164, 10752, v164
	v_xor_b32_e32 v170, 64, v165
	v_lshl_add_u32 v166, v1, 1, v166
	s_add_u32 s48, s74, s0
	s_addc_u32 s49, s75, 0
	s_mov_b32 s42, 0
	s_mov_b32 s58, 0
	s_mov_b32 s56, 0
	s_branch .Lsc_c_bar
